# mLSTM chain phase C: both read-wait-MFMA clusters de-serialised (all fragment reads issued up front, counted lgkmcnt waits, same accumulation order)
# baseline (speedup 1.0000x reference)
; #define MFMA(a, b, c) __builtin_amdgcn_mfma_f32_32x32x16_bf16((a), (b), (c), 0, 0, 0)
; DI int crow(int e, int h) { return (e & 3) + 8 * (e >> 2) + 4 * h; }
; DI void mlstm_chain(const Params& p, int layer, char* smem, VBC& vc, int chain) {
;     ...
;             const float bt = s_b[t], mtt = s_mt[t], wit = s_wi[t];
;             bf16x8 qfr[4];
; #pragma unroll
;             for (int ks = 0; ks < 4; ++ks) qfr[ks] = ld8(sQ + t * AST + ks * 16 + h * 8);
;             bf16x8 pf[2][2];
;             float dsum = 0.f;
;             {
;                 f32x16 sx[2];
; #pragma unroll
;                 for (int si = 0; si < 2; ++si)
; #pragma unroll
;                     for (int e = 0; e < 16; ++e) sx[si][e] = 0.f;
; #pragma unroll
;                 for (int ks = 0; ks < 4; ++ks)
; #pragma unroll
;                     for (int si = 0; si < 2; ++si) sx[si] = MFMA(ld8(sK + (si * 32 + r) * AST + ks * 16 + h * 8), qfr[ks], sx[si]);
; #pragma unroll
;                 for (int si = 0; si < 2; ++si) {
; #pragma unroll
;                     for (int e = 0; e < 16; ++e) {
;                         const int sidx = si * 32 + crow(e, h);
;                         const bool valid = dir ? (sidx >= t) : (sidx <= t);
;                         const float dm = valid ? __expf(bt + s_a[sidx] - mtt) : 0.f;
.LBB0_833:
	ds_read_b128 v[34:37], v107 offset:9216
	ds_read_b128 v[38:41], v124
	ds_read_b128 v[130:133], v107 offset:9248
	ds_read_b128 v[134:137], v124 offset:32
	ds_read_b128 v[162:165], v107 offset:13824
	ds_read_b128 v[166:169], v107 offset:13856
	ds_read_b128 v[170:173], v107 offset:9280
	ds_read_b128 v[174:177], v124 offset:64
	ds_read_b128 v[178:181], v107 offset:13888
	ds_read_b128 v[182:185], v107 offset:9312
	ds_read_b128 v[186:189], v124 offset:96
	ds_read_b128 v[138:141], v107 offset:13920
	ds_read_b32 v108, v123 offset:38144
	ds_read2st64_b32 v[110:111], v123 offset0:146 offset1:148
	s_waitcnt lgkmcnt(12)
	v_mfma_f32_32x32x16_bf16 v[50:65], v[34:37], v[38:41], 0
	s_waitcnt lgkmcnt(10)
	v_mfma_f32_32x32x16_bf16 v[50:65], v[130:133], v[134:137], v[50:65]
	s_waitcnt lgkmcnt(9)
	v_mfma_f32_32x32x16_bf16 v[34:49], v[162:165], v[38:41], 0
	s_waitcnt lgkmcnt(8)
	v_mfma_f32_32x32x16_bf16 v[34:49], v[166:169], v[134:137], v[34:49]
	s_waitcnt lgkmcnt(6)
	v_mfma_f32_32x32x16_bf16 v[50:65], v[170:173], v[174:177], v[50:65]
	s_waitcnt lgkmcnt(5)
	v_mfma_f32_32x32x16_bf16 v[34:49], v[178:181], v[174:177], v[34:49]
	s_waitcnt lgkmcnt(3)
	v_mfma_f32_32x32x16_bf16 v[50:65], v[182:185], v[186:189], v[50:65]
	s_waitcnt lgkmcnt(2)
	v_mfma_f32_32x32x16_bf16 v[34:49], v[138:141], v[186:189], v[34:49]
	v_mov_b32_e32 v129, 0
	v_mov_b32_e32 v130, 0
	ds_read_b128 v[162:165], v104 offset:37632
	ds_read_b128 v[166:169], v104 offset:37664
	ds_read_b128 v[170:173], v104 offset:37696
	ds_read_b128 v[174:177], v104 offset:37728
	ds_read_b128 v[178:181], v104 offset:37760
	ds_read_b128 v[182:185], v104 offset:37792
	ds_read_b128 v[186:189], v104 offset:37824
	ds_read_b128 v[190:193], v104 offset:37856
	s_waitcnt lgkmcnt(0)
	v_add_f32_e32 v130, v110, v162
	v_add_f32_e32 v131, v110, v163
	v_add_f32_e32 v129, v110, v164
	v_add_f32_e32 v133, v110, v165
	v_add_f32_e32 v132, v110, v166
	v_add_f32_e32 v135, v110, v167
	v_add_f32_e32 v134, v110, v168
	v_add_f32_e32 v137, v110, v169
	v_add_f32_e32 v136, v110, v170
	v_add_f32_e32 v139, v110, v171
	v_add_f32_e32 v138, v110, v172
	v_add_f32_e32 v141, v110, v173
	v_add_f32_e32 v140, v110, v174
	v_add_f32_e32 v143, v110, v175
	v_add_f32_e32 v142, v110, v176
	v_add_f32_e32 v145, v110, v177
	v_add_f32_e32 v144, v110, v178
	v_add_f32_e32 v147, v110, v179
	v_add_f32_e32 v146, v110, v180
	v_add_f32_e32 v149, v110, v181
	v_add_f32_e32 v148, v110, v182
	v_add_f32_e32 v151, v110, v183
	v_add_f32_e32 v150, v110, v184
	v_add_f32_e32 v153, v110, v185
	v_add_f32_e32 v152, v110, v186
	v_add_f32_e32 v155, v110, v187
	v_add_f32_e32 v154, v110, v188
	v_add_f32_e32 v157, v110, v189
	v_add_f32_e32 v156, v110, v190
	v_add_f32_e32 v159, v110, v191
	v_add_f32_e32 v158, v110, v192
	v_add_f32_e32 v160, v110, v193
	v_sub_f32_e32 v130, v130, v111
	v_sub_f32_e32 v131, v131, v111
	v_sub_f32_e32 v129, v129, v111
	v_sub_f32_e32 v133, v133, v111
	v_sub_f32_e32 v132, v132, v111
	v_sub_f32_e32 v135, v135, v111
	v_sub_f32_e32 v134, v134, v111
	v_sub_f32_e32 v137, v137, v111
	v_sub_f32_e32 v136, v136, v111
	v_sub_f32_e32 v139, v139, v111
	v_sub_f32_e32 v138, v138, v111
	v_sub_f32_e32 v141, v141, v111
	v_sub_f32_e32 v140, v140, v111
	v_sub_f32_e32 v143, v143, v111
	v_sub_f32_e32 v142, v142, v111
	v_sub_f32_e32 v145, v145, v111
	v_sub_f32_e32 v144, v144, v111
	v_sub_f32_e32 v147, v147, v111
	v_sub_f32_e32 v146, v146, v111
	v_sub_f32_e32 v149, v149, v111
	v_sub_f32_e32 v148, v148, v111
	v_sub_f32_e32 v151, v151, v111
	v_sub_f32_e32 v150, v150, v111
	v_sub_f32_e32 v153, v153, v111
	v_sub_f32_e32 v152, v152, v111
	v_sub_f32_e32 v155, v155, v111
	v_sub_f32_e32 v154, v154, v111
	v_sub_f32_e32 v157, v157, v111
	v_sub_f32_e32 v156, v156, v111
	v_sub_f32_e32 v159, v159, v111
	v_sub_f32_e32 v158, v158, v111
	v_sub_f32_e32 v160, v160, v111
	v_mul_f32_e32 v130, 0x3fb8aa3b, v130
	v_mul_f32_e32 v131, 0x3fb8aa3b, v131
	v_mul_f32_e32 v129, 0x3fb8aa3b, v129
	v_mul_f32_e32 v133, 0x3fb8aa3b, v133
	v_mul_f32_e32 v132, 0x3fb8aa3b, v132
	v_mul_f32_e32 v135, 0x3fb8aa3b, v135
	v_mul_f32_e32 v134, 0x3fb8aa3b, v134
	v_mul_f32_e32 v137, 0x3fb8aa3b, v137
	v_mul_f32_e32 v136, 0x3fb8aa3b, v136
	v_mul_f32_e32 v139, 0x3fb8aa3b, v139
	v_mul_f32_e32 v138, 0x3fb8aa3b, v138
	v_mul_f32_e32 v141, 0x3fb8aa3b, v141
	v_mul_f32_e32 v140, 0x3fb8aa3b, v140
	v_mul_f32_e32 v143, 0x3fb8aa3b, v143
	v_mul_f32_e32 v142, 0x3fb8aa3b, v142
	v_mul_f32_e32 v145, 0x3fb8aa3b, v145
	v_mul_f32_e32 v144, 0x3fb8aa3b, v144
	v_mul_f32_e32 v147, 0x3fb8aa3b, v147
	v_mul_f32_e32 v146, 0x3fb8aa3b, v146
	v_mul_f32_e32 v149, 0x3fb8aa3b, v149
	v_mul_f32_e32 v148, 0x3fb8aa3b, v148
	v_mul_f32_e32 v151, 0x3fb8aa3b, v151
	v_mul_f32_e32 v150, 0x3fb8aa3b, v150
	v_mul_f32_e32 v153, 0x3fb8aa3b, v153
	v_mul_f32_e32 v152, 0x3fb8aa3b, v152
	v_mul_f32_e32 v155, 0x3fb8aa3b, v155
	v_mul_f32_e32 v154, 0x3fb8aa3b, v154
	v_mul_f32_e32 v157, 0x3fb8aa3b, v157
	v_mul_f32_e32 v156, 0x3fb8aa3b, v156
	v_mul_f32_e32 v159, 0x3fb8aa3b, v159
	v_mul_f32_e32 v158, 0x3fb8aa3b, v158
	v_mul_f32_e32 v160, 0x3fb8aa3b, v160
	v_exp_f32_e32 v130, v130
	v_exp_f32_e32 v131, v131
	v_exp_f32_e32 v129, v129
	v_exp_f32_e32 v133, v133
	v_exp_f32_e32 v132, v132
	v_exp_f32_e32 v135, v135
	v_exp_f32_e32 v134, v134
	v_exp_f32_e32 v137, v137
	v_exp_f32_e32 v136, v136
	v_exp_f32_e32 v139, v139
	v_exp_f32_e32 v138, v138
	v_exp_f32_e32 v141, v141
	v_exp_f32_e32 v140, v140
	v_exp_f32_e32 v143, v143
	v_exp_f32_e32 v142, v142
	v_exp_f32_e32 v145, v145
	v_exp_f32_e32 v144, v144
	v_exp_f32_e32 v147, v147
	v_exp_f32_e32 v146, v146
	v_exp_f32_e32 v149, v149
	v_exp_f32_e32 v148, v148
	v_exp_f32_e32 v151, v151
	v_exp_f32_e32 v150, v150
	v_exp_f32_e32 v153, v153
	v_exp_f32_e32 v152, v152
; #define MFMA(a, b, c) __builtin_amdgcn_mfma_f32_32x32x16_bf16((a), (b), (c), 0, 0, 0)
; DI int crow(int e, int h) { return (e & 3) + 8 * (e >> 2) + 4 * h; }
; DI void mlstm_chain(const Params& p, int layer, char* smem, VBC& vc, int chain) {
;     ...
;                     for (int e = 0; e < 16; ++e) {
;                         const int sidx = si * 32 + crow(e, h);
;                         const bool valid = dir ? (sidx >= t) : (sidx <= t);
;                         const float dm = valid ? __expf(bt + s_a[sidx] - mtt) : 0.f;
;                         const float pv = sx[si][e] * dm; sx[si][e] = pv; dsum += pv;
;                     }
;                     pf[si][0] = pack8(sx[si], 0); pf[si][1] = pack8(sx[si], 1);
;                 }
;             }
;             dsum += __shfl_xor(dsum, 32);
;             f32x16 Z;
; #pragma unroll
;             for (int e = 0; e < 16; ++e) Z[e] = 0.f;
; #pragma unroll
;             for (int dt = 0; dt < 2; ++dt)
; #pragma unroll
;                 for (int sp = 0; sp < 2; ++sp) {
;                     const u16* qp = sQ + t * AST + dt * 32 + sp * 16 + 4 * h;
;                     Z = MFMA(pack8(Cst[dt], sp), ld4x2(qp, qp + 8), Z);
	v_exp_f32_e32 v155, v155
	v_exp_f32_e32 v154, v154
	v_exp_f32_e32 v157, v157
	v_exp_f32_e32 v156, v156
	v_exp_f32_e32 v159, v159
	v_exp_f32_e32 v158, v158
	v_exp_f32_e32 v160, v160
	v_cndmask_b32_e64 v130, 0, v130, s[42:43]
	v_cndmask_b32_e64 v131, 0, v131, s[58:59]
	v_cndmask_b32_e64 v129, 0, v129, s[72:73]
	v_cndmask_b32_e64 v133, 0, v133, s[74:75]
	v_cndmask_b32_e64 v132, 0, v132, s[76:77]
	v_cndmask_b32_e64 v135, 0, v135, s[78:79]
	v_cndmask_b32_e64 v134, 0, v134, s[80:81]
	v_cndmask_b32_e64 v137, 0, v137, s[82:83]
	v_cndmask_b32_e64 v136, 0, v136, s[84:85]
	v_cndmask_b32_e64 v139, 0, v139, s[86:87]
	v_cndmask_b32_e64 v138, 0, v138, s[88:89]
	v_cndmask_b32_e64 v141, 0, v141, s[90:91]
	v_cndmask_b32_e64 v140, 0, v140, s[22:23]
	v_cndmask_b32_e64 v143, 0, v143, s[96:97]
	v_cndmask_b32_e64 v150, 0, v150, s[2:3]
	v_cndmask_b32_e64 v153, 0, v153, s[4:5]
	v_cndmask_b32_e64 v152, 0, v152, s[6:7]
	v_cndmask_b32_e64 v155, 0, v155, s[8:9]
	v_cndmask_b32_e64 v154, 0, v154, s[10:11]
	v_cndmask_b32_e64 v157, 0, v157, s[12:13]
	v_cndmask_b32_e64 v156, 0, v156, s[14:15]
	v_cndmask_b32_e64 v159, 0, v159, s[16:17]
	v_cndmask_b32_e64 v158, 0, v158, s[18:19]
	v_cndmask_b32_e64 v160, 0, v160, s[20:21]
	v_readlane_b32 s24, v250, 9
	v_readlane_b32 s25, v250, 10
	s_nop 1
	v_cndmask_b32_e64 v142, 0, v142, s[24:25]
	v_readlane_b32 s24, v250, 11
	v_readlane_b32 s25, v250, 12
	s_nop 1
	v_cndmask_b32_e64 v145, 0, v145, s[24:25]
	v_readlane_b32 s24, v250, 13
	v_readlane_b32 s25, v250, 14
	s_nop 1
	v_cndmask_b32_e64 v144, 0, v144, s[24:25]
	v_readlane_b32 s24, v250, 15
	v_readlane_b32 s25, v250, 16
	s_nop 1
	v_cndmask_b32_e64 v147, 0, v147, s[24:25]
	v_readlane_b32 s24, v250, 17
	v_readlane_b32 s25, v250, 18
	s_nop 1
	v_cndmask_b32_e64 v146, 0, v146, s[24:25]
	v_readlane_b32 s24, v250, 19
	v_readlane_b32 s25, v250, 20
	s_nop 1
	v_cndmask_b32_e64 v149, 0, v149, s[24:25]
	v_readlane_b32 s24, v250, 21
	v_readlane_b32 s25, v250, 22
	s_nop 1
	v_cndmask_b32_e64 v148, 0, v148, s[24:25]
	v_readlane_b32 s24, v250, 23
	v_readlane_b32 s25, v250, 24
	s_nop 1
	v_cndmask_b32_e64 v151, 0, v151, s[24:25]
	s_waitcnt lgkmcnt(0)
	v_fma_f32 v110, v50, v130, 0
	v_fmac_f32_e32 v110, v51, v131
	v_fmac_f32_e32 v110, v52, v129
	v_fmac_f32_e32 v110, v53, v133
	v_fmac_f32_e32 v110, v54, v132
	v_fmac_f32_e32 v110, v55, v135
	v_fmac_f32_e32 v110, v56, v134
	v_fmac_f32_e32 v110, v57, v137
	v_fmac_f32_e32 v110, v58, v136
	v_fmac_f32_e32 v110, v59, v139
	v_fmac_f32_e32 v110, v60, v138
	v_fmac_f32_e32 v110, v61, v141
	v_fmac_f32_e32 v110, v62, v140
	v_fmac_f32_e32 v110, v63, v143
	v_fmac_f32_e32 v110, v64, v142
	v_fmac_f32_e32 v110, v65, v145
	v_fmac_f32_e32 v110, v34, v144
	v_fmac_f32_e32 v110, v35, v147
	v_fmac_f32_e32 v110, v36, v146
	v_fmac_f32_e32 v110, v37, v149
	v_fmac_f32_e32 v110, v38, v148
	v_fmac_f32_e32 v110, v39, v151
	v_fmac_f32_e32 v110, v40, v150
	v_fmac_f32_e32 v110, v41, v153
	v_fmac_f32_e32 v110, v42, v152
	v_fmac_f32_e32 v110, v43, v155
	v_mul_f32_e32 v161, v50, v130
	v_mul_f32_e32 v50, v51, v131
	v_mul_f32_e32 v51, v52, v129
	v_mul_f32_e32 v52, v53, v133
	v_mul_f32_e32 v53, v54, v132
	v_mul_f32_e32 v54, v55, v135
	v_mul_f32_e32 v55, v56, v134
	v_mul_f32_e32 v56, v57, v137
	v_mul_f32_e32 v57, v58, v136
	v_mul_f32_e32 v136, v34, v144
	v_mul_f32_e32 v34, v35, v147
	v_mul_f32_e32 v35, v36, v146
	v_mul_f32_e32 v36, v37, v149
	v_fmac_f32_e32 v110, v44, v154
	v_mul_f32_e32 v129, v59, v139
	v_fmac_f32_e32 v110, v45, v157
	v_cvt_pk_bf16_f32 v59, v51, v52
	v_cvt_pk_bf16_f32 v51, v35, v36
	v_and_b32_e32 v35, 64, v237
	v_fmac_f32_e32 v110, v46, v156
	v_cvt_pk_bf16_f32 v58, v161, v50
	v_cvt_pk_bf16_f32 v50, v136, v34
	v_xor_b32_e32 v34, 32, v237
	v_add_u32_e32 v35, 64, v35
	v_fmac_f32_e32 v110, v47, v159
	v_cmp_lt_i32_e32 vcc, v34, v35
	v_fmac_f32_e32 v110, v48, v158
	v_mul_f32_e32 v37, v38, v148
	v_cndmask_b32_e32 v34, v237, v34, vcc
	v_mul_f32_e32 v38, v39, v151
	v_fmac_f32_e32 v110, v49, v160
	v_lshlrev_b32_e32 v34, 2, v34
	v_mul_f32_e32 v130, v60, v138
	v_mul_f32_e32 v131, v61, v141
	v_mul_f32_e32 v132, v62, v140
	v_mul_f32_e32 v133, v63, v143
	v_mul_f32_e32 v39, v40, v150
	v_mul_f32_e32 v40, v41, v153
	v_mul_f32_e32 v41, v42, v152
	v_mul_f32_e32 v42, v43, v155
	v_cvt_pk_bf16_f32 v62, v57, v129
	v_cvt_pk_bf16_f32 v52, v37, v38
	ds_bpermute_b32 v129, v34, v110
	v_cvt_pk_bf16_f32 v34, v2, v3
	v_cvt_pk_bf16_f32 v35, v4, v5
	v_cvt_pk_bf16_f32 v36, v6, v7
	v_cvt_pk_bf16_f32 v37, v8, v9
	v_mul_f32_e32 v134, v64, v142
	v_cvt_pk_bf16_f32 v60, v53, v54
	v_cvt_pk_bf16_f32 v63, v130, v131
	v_cvt_pk_bf16_f32 v64, v132, v133
	v_cvt_pk_bf16_f32 v53, v39, v40
	v_cvt_pk_bf16_f32 v54, v41, v42
	ds_read2_b64 v[38:41], v126 offset1:2
	ds_read2_b64 v[130:133], v126 offset0:4 offset1:6
	v_mul_f32_e32 v43, v44, v154
	v_mul_f32_e32 v44, v45, v157
	v_mul_f32_e32 v45, v46, v156
	v_mul_f32_e32 v46, v47, v159
	v_mul_f32_e32 v47, v48, v158
	v_mul_f32_e32 v48, v49, v160
	v_cvt_pk_bf16_f32 v61, v55, v56
	v_cvt_pk_bf16_f32 v55, v43, v44
	v_cvt_pk_bf16_f32 v56, v45, v46
	v_cvt_pk_bf16_f32 v57, v47, v48
	s_waitcnt lgkmcnt(1)
	v_mfma_f32_32x32x16_bf16 v[34:49], v[34:37], v[38:41], 0
	v_mul_f32_e32 v135, v65, v145
	v_cvt_pk_bf16_f32 v65, v134, v135
	v_cvt_pk_bf16_f32 v134, v10, v11
	v_cvt_pk_bf16_f32 v135, v12, v13
	v_cvt_pk_bf16_f32 v136, v14, v15
	v_cvt_pk_bf16_f32 v137, v16, v17
	s_waitcnt lgkmcnt(0)
	s_nop 0
	v_mfma_f32_32x32x16_bf16 v[34:49], v[134:137], v[130:133], v[34:49]
	v_cvt_pk_bf16_f32 v130, v18, v19
	v_cvt_pk_bf16_f32 v131, v20, v21
	v_cvt_pk_bf16_f32 v132, v22, v23
	v_cvt_pk_bf16_f32 v133, v24, v25
	ds_read2_b64 v[134:137], v126 offset0:8 offset1:10
	s_waitcnt lgkmcnt(0)
; #define MFMA(a, b, c) __builtin_amdgcn_mfma_f32_32x32x16_bf16((a), (b), (c), 0, 0, 0)
; DI unsigned pk2(float a, float b) { f32x2 v = {a, b}; bf2_t r = __builtin_convertvector(v, bf2_t); return __builtin_bit_cast(unsigned, r); }
; DI float bflo(unsigned v) { return __uint_as_float(v << 16); }
; DI float bfhi(unsigned v) { return __uint_as_float(v & 0xffff0000u); }
; DI void st_bf4(u16* dst, float a, float b, float c, float d) { uint2 u = {pk2(a, b), pk2(c, d)}; *(uint2*)dst = u; }
; DI void mlstm_chain(const Params& p, int layer, char* smem, VBC& vc, int chain) {
;     ...
;                     Z = MFMA(pack8(Cst[dt], sp), ld4x2(qp, qp + 8), Z);
;                 }
; #pragma unroll
;             for (int e = 0; e < 16; ++e) Z[e] *= wit;
; #pragma unroll
;             for (int kk = 0; kk < 4; ++kk) {
;                 const int si = kk >> 1, sp = kk & 1;
;                 Z = MFMA(ld8(sVT + (vh * 32 + r) * AST + si * 32 + sp * 16 + 8 * h), pf[si][sp], Z);
;             }
;             const float den = wit * s_nq[t] + dsum;
;             const float inv = 1.f / fmaxf(fabsf(den), __expf(-mtt));
;             u16* hp = HD + (size_t)(prow0 + t) * 384 + hd * 64 + vh * 32 + 4 * h;
; #pragma unroll
;             for (int g = 0; g < 4; ++g) st_bf4(hp + 8 * g, Z[4 * g] * inv, Z[4 * g + 1] * inv, Z[4 * g + 2] * inv, Z[4 * g + 3] * inv);
;             const float decay = s_sc[0];
;             bf16x8 wv[4];
; #pragma unroll
;             for (int ks = 0; ks < 4; ++ks) {
;                 uint4 vv = *(const uint4*)(sVT + (vh * 32 + r) * AST + ks * 16 + h * 8);
;                 float4 w0 = *(const float4*)(s_w + ks * 16 + 4 * h), w1 = *(const float4*)(s_w + ks * 16 + 8 + 4 * h);
;                 uint4 u;
;                 u.x = pk2(bflo(vv.x) * w0.x, bfhi(vv.x) * w0.y); u.y = pk2(bflo(vv.y) * w0.z, bfhi(vv.y) * w0.w);
;                 u.z = pk2(bflo(vv.z) * w1.x, bfhi(vv.z) * w1.y); u.w = pk2(bflo(vv.w) * w1.z, bfhi(vv.w) * w1.w);
;                 wv[ks] = __builtin_bit_cast(bf16x8, u);
;             }
; #pragma unroll
;             for (int dt = 0; dt < 2; ++dt)
; #pragma unroll
;                 for (int e = 0; e < 16; ++e) Cst[dt][e] *= decay;
	v_mfma_f32_32x32x16_bf16 v[34:49], v[130:133], v[134:137], v[34:49]
	v_cvt_pk_bf16_f32 v130, v26, v27
	v_cvt_pk_bf16_f32 v131, v28, v29
	v_cvt_pk_bf16_f32 v132, v30, v31
	v_cvt_pk_bf16_f32 v133, v32, v33
	ds_read2_b64 v[134:137], v126 offset0:12 offset1:14
	s_waitcnt lgkmcnt(0)
	v_mfma_f32_32x32x16_bf16 v[34:49], v[130:133], v[134:137], v[34:49]
	ds_read_b128 v[130:133], v106 offset:27648
	ds_read_b128 v[134:137], v106 offset:27680
	s_nop 9
	v_pk_mul_f32 v[48:49], v[108:109], v[48:49] op_sel_hi:[0,1]
	v_pk_mul_f32 v[46:47], v[108:109], v[46:47] op_sel_hi:[0,1]
	v_pk_mul_f32 v[44:45], v[108:109], v[44:45] op_sel_hi:[0,1]
	v_pk_mul_f32 v[42:43], v[108:109], v[42:43] op_sel_hi:[0,1]
	v_pk_mul_f32 v[40:41], v[108:109], v[40:41] op_sel_hi:[0,1]
	v_pk_mul_f32 v[38:39], v[108:109], v[38:39] op_sel_hi:[0,1]
	v_pk_mul_f32 v[36:37], v[108:109], v[36:37] op_sel_hi:[0,1]
	v_pk_mul_f32 v[34:35], v[108:109], v[34:35] op_sel_hi:[0,1]
	s_waitcnt lgkmcnt(1)
	s_nop 0
	v_mfma_f32_32x32x16_bf16 v[34:49], v[130:133], v[58:61], v[34:49]
	ds_read_b128 v[58:61], v106 offset:27712
	s_waitcnt lgkmcnt(1)
	v_mfma_f32_32x32x16_bf16 v[34:49], v[134:137], v[62:65], v[34:49]
	s_waitcnt lgkmcnt(0)
	v_mfma_f32_32x32x16_bf16 v[34:49], v[58:61], v[50:53], v[34:49]
	ds_read_b128 v[50:53], v106 offset:27744
	s_waitcnt lgkmcnt(0)
	v_mfma_f32_32x32x16_bf16 v[34:49], v[50:53], v[54:57], v[34:49]
	ds_read_b32 v51, v127 offset:38656
	v_add_f32_e32 v50, v110, v129
	s_waitcnt lgkmcnt(0)
	v_fmac_f32_e32 v50, v108, v51
	v_mul_f32_e32 v51, 0xbfb8aa3b, v111
	v_exp_f32_e32 v51, v51
	s_nop 0
	v_max_f32_e64 v50, |v50|, v51
	v_div_scale_f32 v51, s[0:1], v50, v50, 1.0
	v_rcp_f32_e32 v52, v51
	s_movk_i32 s0, 0x300
	v_fma_f32 v53, -v51, v52, 1.0
	v_fmac_f32_e32 v52, v53, v52
	v_div_scale_f32 v53, vcc, 1.0, v50, 1.0
	v_mul_f32_e32 v54, v53, v52
	v_fma_f32 v55, -v51, v54, v53
	v_fmac_f32_e32 v54, v55, v52
	v_fma_f32 v51, -v51, v54, v53
	v_div_fmas_f32 v51, v51, v52, v54
	v_div_fixup_f32 v50, v51, v50, 1.0
	v_add_u32_e32 v51, s62, v122
	v_pk_mul_f32 v[34:35], v[34:35], v[50:51] op_sel_hi:[1,0]
	v_pk_mul_f32 v[36:37], v[36:37], v[50:51] op_sel_hi:[1,0]
	v_mad_i64_i32 v[52:53], s[0:1], v51, s0, v[102:103]
	v_cvt_pk_bf16_f32 v34, v34, v35
	v_cvt_pk_bf16_f32 v35, v36, v37
	global_store_dwordx2 v[52:53], v[34:35], off
	v_pk_mul_f32 v[34:35], v[38:39], v[50:51] op_sel_hi:[1,0]
	v_pk_mul_f32 v[36:37], v[40:41], v[50:51] op_sel_hi:[1,0]
	v_cvt_pk_bf16_f32 v34, v34, v35
	v_cvt_pk_bf16_f32 v35, v36, v37
	global_store_dwordx2 v[52:53], v[34:35], off offset:16
	v_pk_mul_f32 v[34:35], v[42:43], v[50:51] op_sel_hi:[1,0]
	v_pk_mul_f32 v[36:37], v[44:45], v[50:51] op_sel_hi:[1,0]
	v_cvt_pk_bf16_f32 v34, v34, v35
	v_cvt_pk_bf16_f32 v35, v36, v37
	global_store_dwordx2 v[52:53], v[34:35], off offset:32
	v_pk_mul_f32 v[34:35], v[46:47], v[50:51] op_sel_hi:[1,0]
	v_pk_mul_f32 v[36:37], v[48:49], v[50:51] op_sel_hi:[1,0]
	v_cvt_pk_bf16_f32 v34, v34, v35
	v_cvt_pk_bf16_f32 v35, v36, v37
	global_store_dwordx2 v[52:53], v[34:35], off offset:48
	v_mov_b32_e32 v34, s33
	ds_read_b32 v50, v34 offset:39168
	ds_read_b128 v[34:37], v104 offset:38400
	ds_read_b128 v[38:41], v104 offset:38432
	v_lshlrev_b32_e32 v42, 16, v130
	v_and_b32_e32 v43, 0xffff0000, v130
	s_waitcnt lgkmcnt(1)
	v_pk_mul_f32 v[34:35], v[34:35], v[42:43]
	v_lshlrev_b32_e32 v42, 16, v131
	v_and_b32_e32 v43, 0xffff0000, v131
	v_pk_mul_f32 v[36:37], v[36:37], v[42:43]
	v_cvt_pk_bf16_f32 v34, v34, v35
	v_cvt_pk_bf16_f32 v35, v36, v37
	v_lshlrev_b32_e32 v36, 16, v132
	v_and_b32_e32 v37, 0xffff0000, v132
	s_waitcnt lgkmcnt(0)
	v_pk_mul_f32 v[36:37], v[38:39], v[36:37]
	v_lshlrev_b32_e32 v38, 16, v133
	v_and_b32_e32 v39, 0xffff0000, v133
	v_pk_mul_f32 v[38:39], v[40:41], v[38:39]
	v_cvt_pk_bf16_f32 v36, v36, v37
	v_cvt_pk_bf16_f32 v37, v38, v39
	ds_read_b128 v[38:41], v106 offset:27680
	ds_read_b128 v[42:45], v106 offset:27712
	ds_read_b128 v[46:49], v104 offset:38464
	v_pk_mul_f32 v[16:17], v[16:17], v[50:51] op_sel_hi:[1,0]
	v_pk_mul_f32 v[14:15], v[14:15], v[50:51] op_sel_hi:[1,0]
	s_waitcnt lgkmcnt(2)
	v_lshlrev_b32_e32 v52, 16, v38
	v_and_b32_e32 v53, 0xffff0000, v38
	s_waitcnt lgkmcnt(0)
; #define MFMA(a, b, c) __builtin_amdgcn_mfma_f32_32x32x16_bf16((a), (b), (c), 0, 0, 0)
; DI unsigned pk2(float a, float b) { f32x2 v = {a, b}; bf2_t r = __builtin_convertvector(v, bf2_t); return __builtin_bit_cast(unsigned, r); }
; DI float bflo(unsigned v) { return __uint_as_float(v << 16); }
; DI float bfhi(unsigned v) { return __uint_as_float(v & 0xffff0000u); }
; DI int lane_id() { int l; asm volatile("v_mbcnt_lo_u32_b32 %0, -1, 0\n\tv_mbcnt_hi_u32_b32 %0, -1, %0" : "=v"(l)); return l; }
; DI void vb_sync(VBC& vc) {
;     ...
;     asm volatile("s_waitcnt lgkmcnt(0)" ::: "memory");
;     if (lane_id() == 0) __hip_atomic_fetch_add(vc.cnt, 1u, __ATOMIC_RELAXED, __HIP_MEMORY_SCOPE_WORKGROUP);
; DI void mlstm_chain(const Params& p, int layer, char* smem, VBC& vc, int chain) {
;     ...
;             for (int ks = 0; ks < 4; ++ks) {
;                 uint4 vv = *(const uint4*)(sVT + (vh * 32 + r) * AST + ks * 16 + h * 8);
;                 float4 w0 = *(const float4*)(s_w + ks * 16 + 4 * h), w1 = *(const float4*)(s_w + ks * 16 + 8 + 4 * h);
;                 uint4 u;
;                 u.x = pk2(bflo(vv.x) * w0.x, bfhi(vv.x) * w0.y); u.y = pk2(bflo(vv.y) * w0.z, bfhi(vv.y) * w0.w);
;                 u.z = pk2(bflo(vv.z) * w1.x, bfhi(vv.z) * w1.y); u.w = pk2(bflo(vv.w) * w1.z, bfhi(vv.w) * w1.w);
;                 wv[ks] = __builtin_bit_cast(bf16x8, u);
;             }
; #pragma unroll
;             for (int dt = 0; dt < 2; ++dt)
; #pragma unroll
;                 for (int e = 0; e < 16; ++e) Cst[dt][e] *= decay;
; #pragma unroll
;             for (int ks = 0; ks < 4; ++ks)
; #pragma unroll
;                 for (int dt = 0; dt < 2; ++dt) Cst[dt] = MFMA(ld8(sKT + (dt * 32 + r) * AST + ks * 16 + h * 8), wv[ks], Cst[dt]);
	v_pk_mul_f32 v[46:47], v[46:47], v[52:53]
	ds_read_b128 v[52:55], v104 offset:38496
	v_lshlrev_b32_e32 v38, 16, v39
	v_and_b32_e32 v39, 0xffff0000, v39
	v_pk_mul_f32 v[38:39], v[48:49], v[38:39]
	v_cvt_pk_bf16_f32 v46, v46, v47
	v_cvt_pk_bf16_f32 v47, v38, v39
	v_lshlrev_b32_e32 v38, 16, v40
	v_and_b32_e32 v39, 0xffff0000, v40
	s_waitcnt lgkmcnt(0)
	v_pk_mul_f32 v[38:39], v[52:53], v[38:39]
	v_lshlrev_b32_e32 v52, 16, v42
	v_cvt_pk_bf16_f32 v48, v38, v39
	v_lshlrev_b32_e32 v38, 16, v41
	v_and_b32_e32 v39, 0xffff0000, v41
	v_pk_mul_f32 v[38:39], v[54:55], v[38:39]
	v_and_b32_e32 v53, 0xffff0000, v42
	v_cvt_pk_bf16_f32 v49, v38, v39
	ds_read_b128 v[38:41], v104 offset:38528
	v_lshlrev_b32_e32 v42, 16, v43
	v_and_b32_e32 v43, 0xffff0000, v43
	v_pk_mul_f32 v[12:13], v[12:13], v[50:51] op_sel_hi:[1,0]
	v_pk_mul_f32 v[10:11], v[10:11], v[50:51] op_sel_hi:[1,0]
	s_waitcnt lgkmcnt(0)
	v_pk_mul_f32 v[38:39], v[38:39], v[52:53]
	v_pk_mul_f32 v[40:41], v[40:41], v[42:43]
	v_cvt_pk_bf16_f32 v38, v38, v39
	v_cvt_pk_bf16_f32 v39, v40, v41
	ds_read_b128 v[40:43], v104 offset:38560
	v_lshlrev_b32_e32 v52, 16, v44
	v_and_b32_e32 v53, 0xffff0000, v44
	v_lshlrev_b32_e32 v44, 16, v45
	v_and_b32_e32 v45, 0xffff0000, v45
	s_waitcnt lgkmcnt(0)
	v_pk_mul_f32 v[40:41], v[40:41], v[52:53]
	v_pk_mul_f32 v[42:43], v[42:43], v[44:45]
	v_cvt_pk_bf16_f32 v40, v40, v41
	v_cvt_pk_bf16_f32 v41, v42, v43
	ds_read_b128 v[42:45], v106 offset:27744
	ds_read_b128 v[52:55], v104 offset:38592
	v_pk_mul_f32 v[8:9], v[8:9], v[50:51] op_sel_hi:[1,0]
	v_pk_mul_f32 v[6:7], v[6:7], v[50:51] op_sel_hi:[1,0]
	v_pk_mul_f32 v[4:5], v[4:5], v[50:51] op_sel_hi:[1,0]
	s_waitcnt lgkmcnt(1)
	v_lshlrev_b32_e32 v56, 16, v42
	v_and_b32_e32 v57, 0xffff0000, v42
	s_waitcnt lgkmcnt(0)
	v_pk_mul_f32 v[52:53], v[52:53], v[56:57]
	v_lshlrev_b32_e32 v56, 16, v44
	v_cvt_pk_bf16_f32 v42, v52, v53
	v_lshlrev_b32_e32 v52, 16, v43
	v_and_b32_e32 v53, 0xffff0000, v43
	v_pk_mul_f32 v[52:53], v[54:55], v[52:53]
	v_and_b32_e32 v57, 0xffff0000, v44
	v_cvt_pk_bf16_f32 v43, v52, v53
	ds_read_b128 v[52:55], v104 offset:38624
	v_pk_mul_f32 v[2:3], v[2:3], v[50:51] op_sel_hi:[1,0]
	v_pk_mul_f32 v[32:33], v[32:33], v[50:51] op_sel_hi:[1,0]
	v_pk_mul_f32 v[30:31], v[30:31], v[50:51] op_sel_hi:[1,0]
	v_pk_mul_f32 v[28:29], v[28:29], v[50:51] op_sel_hi:[1,0]
	s_waitcnt lgkmcnt(0)
	v_pk_mul_f32 v[52:53], v[52:53], v[56:57]
	v_pk_mul_f32 v[26:27], v[26:27], v[50:51] op_sel_hi:[1,0]
	v_cvt_pk_bf16_f32 v44, v52, v53
	v_lshlrev_b32_e32 v52, 16, v45
	v_and_b32_e32 v53, 0xffff0000, v45
	v_pk_mul_f32 v[52:53], v[54:55], v[52:53]
	v_pk_mul_f32 v[24:25], v[24:25], v[50:51] op_sel_hi:[1,0]
	v_cvt_pk_bf16_f32 v45, v52, v53
	v_pk_mul_f32 v[22:23], v[22:23], v[50:51] op_sel_hi:[1,0]
	v_pk_mul_f32 v[20:21], v[20:21], v[50:51] op_sel_hi:[1,0]
	v_pk_mul_f32 v[18:19], v[18:19], v[50:51] op_sel_hi:[1,0]
	ds_read_b128 v[50:53], v107 offset:18432
	ds_read_b128 v[162:165], v107 offset:23040
	ds_read_b128 v[166:169], v107 offset:23072
	ds_read_b128 v[54:57], v107 offset:18464
	ds_read_b128 v[170:173], v107 offset:18496
	ds_read_b128 v[174:177], v107 offset:23104
	ds_read_b128 v[178:181], v107 offset:18528
	ds_read_b128 v[182:185], v107 offset:23136
	s_waitcnt lgkmcnt(7)
	v_mfma_f32_32x32x16_bf16 v[2:17], v[50:53], v[34:37], v[2:17]
	s_waitcnt lgkmcnt(6)
	v_mfma_f32_32x32x16_bf16 v[18:33], v[162:165], v[34:37], v[18:33]
	s_waitcnt lgkmcnt(5)
	v_mfma_f32_32x32x16_bf16 v[18:33], v[166:169], v[46:49], v[18:33]
	s_waitcnt lgkmcnt(4)
	v_mfma_f32_32x32x16_bf16 v[2:17], v[54:57], v[46:49], v[2:17]
	s_waitcnt lgkmcnt(3)
	v_mfma_f32_32x32x16_bf16 v[2:17], v[170:173], v[38:41], v[2:17]
	s_waitcnt lgkmcnt(2)
	v_mfma_f32_32x32x16_bf16 v[18:33], v[174:177], v[38:41], v[18:33]
	s_waitcnt lgkmcnt(1)
	v_mfma_f32_32x32x16_bf16 v[2:17], v[178:181], v[42:45], v[2:17]
	s_waitcnt lgkmcnt(0)
	v_mfma_f32_32x32x16_bf16 v[18:33], v[182:185], v[42:45], v[18:33]
	v_mbcnt_lo_u32_b32 v34, -1, 0
	v_mbcnt_hi_u32_b32 v34, -1, v34
	s_nop 0
	v_cmp_eq_u32_e32 vcc, 0, v34
	s_and_saveexec_b64 s[0:1], vcc
	s_cbranch_execz .LBB0_896
	s_mov_b64 s[24:25], exec
	v_mbcnt_lo_u32_b32 v34, s24, 0
	v_mbcnt_hi_u32_b32 v34, s25, v34
	v_cmp_eq_u32_e32 vcc, 0, v34
	s_and_b64 s[26:27], exec, vcc
	s_mov_b64 exec, s[26:27]
	s_bcnt1_i32_b64 s24, s[24:25]
	v_mov_b32_e32 v34, s35
	v_mov_b32_e32 v35, s24
	ds_add_u32 v34, v35
